# GEMM epilogue: relu canonicalize dropped, store addresses derived from group 0 + scalar offset, tile-top vmcnt(0) moved after accumulator zeroing
# baseline (speedup 1.0000x reference)
; #define PG8_BAR __builtin_amdgcn_s_barrier()
; template <class Epi>
; __device__ __forceinline__ void gemm_phase(LAS unsigned char* lds, const Gemm g, const StaticOrder& S, const Epi& E) {
;     ...
; #pragma unroll
;         for (int a = 0; a < 2; ++a)
; #pragma unroll
;             for (int b = 0; b < 2; ++b)
; #pragma unroll
;                 for (int m = 0; m < 4; ++m)
; #pragma unroll
;                     for (int n = 0; n < 2; ++n) acc[a][b][m][n] = (f32x4){0.f, 0.f, 0.f, 0.f};
;         cur = nxt; cA = nA; cB = nB; ++ui;
;         if (wr == 1) PG8_BAR;
.LBB0_221:
	s_add_u32 s0, s6, 0x80
	s_addc_u32 s1, s7, 0
	s_add_u32 s6, s4, 0x100
	v_mov_b32_e32 v0, 0
	s_addc_u32 s7, s5, 0
	s_mov_b32 s4, 0
	v_mov_b32_e32 v1, v0
	v_mov_b32_e32 v2, v0
	v_mov_b32_e32 v3, v0
	v_mov_b32_e32 v4, v0
	v_mov_b32_e32 v5, v0
	v_mov_b32_e32 v6, v0
	v_mov_b32_e32 v7, v0
	v_mov_b32_e32 v16, v0
	v_mov_b32_e32 v17, v0
	v_mov_b32_e32 v18, v0
	v_mov_b32_e32 v19, v0
	v_mov_b32_e32 v20, v0
	v_mov_b32_e32 v21, v0
	v_mov_b32_e32 v22, v0
	v_mov_b32_e32 v23, v0
	v_mov_b32_e32 v32, v0
	v_mov_b32_e32 v33, v0
	v_mov_b32_e32 v34, v0
	v_mov_b32_e32 v35, v0
	v_mov_b32_e32 v36, v0
	v_mov_b32_e32 v37, v0
	v_mov_b32_e32 v38, v0
	v_mov_b32_e32 v39, v0
	v_mov_b32_e32 v48, v0
	v_mov_b32_e32 v49, v0
	v_mov_b32_e32 v50, v0
	v_mov_b32_e32 v51, v0
	v_mov_b32_e32 v52, v0
	v_mov_b32_e32 v53, v0
	v_mov_b32_e32 v54, v0
	v_mov_b32_e32 v55, v0
	v_mov_b32_e32 v8, v0
	v_mov_b32_e32 v9, v0
	v_mov_b32_e32 v10, v0
	v_mov_b32_e32 v11, v0
	v_mov_b32_e32 v12, v0
	v_mov_b32_e32 v13, v0
	v_mov_b32_e32 v14, v0
	v_mov_b32_e32 v15, v0
	v_mov_b32_e32 v24, v0
	v_mov_b32_e32 v25, v0
	v_mov_b32_e32 v26, v0
	v_mov_b32_e32 v27, v0
	v_mov_b32_e32 v28, v0
	v_mov_b32_e32 v29, v0
	v_mov_b32_e32 v30, v0
	v_mov_b32_e32 v31, v0
	v_mov_b32_e32 v40, v0
	v_mov_b32_e32 v41, v0
	v_mov_b32_e32 v42, v0
	v_mov_b32_e32 v43, v0
	v_mov_b32_e32 v44, v0
	v_mov_b32_e32 v45, v0
	v_mov_b32_e32 v46, v0
	v_mov_b32_e32 v47, v0
	v_mov_b32_e32 v56, v0
	v_mov_b32_e32 v57, v0
	v_mov_b32_e32 v58, v0
	v_mov_b32_e32 v59, v0
	v_mov_b32_e32 v60, v0
	v_mov_b32_e32 v61, v0
	v_mov_b32_e32 v62, v0
	v_mov_b32_e32 v63, v0
	v_mov_b32_e32 v64, v0
	v_mov_b32_e32 v65, v0
	v_mov_b32_e32 v66, v0
	v_mov_b32_e32 v67, v0
	v_mov_b32_e32 v68, v0
	v_mov_b32_e32 v69, v0
	v_mov_b32_e32 v70, v0
	v_mov_b32_e32 v71, v0
	v_mov_b32_e32 v80, v0
	v_mov_b32_e32 v81, v0
	v_mov_b32_e32 v82, v0
	v_mov_b32_e32 v83, v0
	v_mov_b32_e32 v84, v0
	v_mov_b32_e32 v85, v0
	v_mov_b32_e32 v86, v0
	v_mov_b32_e32 v87, v0
	v_mov_b32_e32 v96, v0
	v_mov_b32_e32 v97, v0
	v_mov_b32_e32 v98, v0
	v_mov_b32_e32 v99, v0
	v_mov_b32_e32 v100, v0
	v_mov_b32_e32 v101, v0
	v_mov_b32_e32 v102, v0
	v_mov_b32_e32 v103, v0
	v_mov_b32_e32 v112, v0
	v_mov_b32_e32 v113, v0
	v_mov_b32_e32 v114, v0
	v_mov_b32_e32 v115, v0
	v_mov_b32_e32 v116, v0
	v_mov_b32_e32 v117, v0
	v_mov_b32_e32 v118, v0
	v_mov_b32_e32 v119, v0
	v_mov_b32_e32 v72, v0
	v_mov_b32_e32 v73, v0
	v_mov_b32_e32 v74, v0
	v_mov_b32_e32 v75, v0
	v_mov_b32_e32 v76, v0
	v_mov_b32_e32 v77, v0
	v_mov_b32_e32 v78, v0
	v_mov_b32_e32 v79, v0
	v_mov_b32_e32 v88, v0
	v_mov_b32_e32 v89, v0
	v_mov_b32_e32 v90, v0
	v_mov_b32_e32 v91, v0
	v_mov_b32_e32 v92, v0
	v_mov_b32_e32 v93, v0
	v_mov_b32_e32 v94, v0
	v_mov_b32_e32 v95, v0
	v_mov_b32_e32 v104, v0
	v_mov_b32_e32 v105, v0
	v_mov_b32_e32 v106, v0
	v_mov_b32_e32 v107, v0
	v_mov_b32_e32 v108, v0
	v_mov_b32_e32 v109, v0
	v_mov_b32_e32 v110, v0
	v_mov_b32_e32 v111, v0
	v_mov_b32_e32 v120, v0
	v_mov_b32_e32 v121, v0
	v_mov_b32_e32 v122, v0
	v_mov_b32_e32 v123, v0
	v_mov_b32_e32 v124, v0
	v_mov_b32_e32 v125, v0
	v_mov_b32_e32 v126, v0
	v_mov_b32_e32 v127, v0
	s_waitcnt vmcnt(0)

; __device__ __forceinline__ unsigned cvtpk(float lo, float hi) { f32x2 v = {lo, hi}; bf16x2_t b = __builtin_convertvector(v, bf16x2_t); return __builtin_bit_cast(unsigned, b); }
;     __device__ __forceinline__ void operator()(AccRef acc, const Unit& u, int wr, int wc, int fr, int fq) const {
;     ...
;                 for (int m = 0; m < 4; ++m) { const int row = row0 + ai * HALF + m * 16; bf16_t* rowp = O + (size_t)row * ldc + col0;
;                     float rs = 1.f; if (nrm) rs = rsqrtf((float)rin[row] * RSS_INV + EPS);
; #pragma unroll
;                     for (int bj = 0; bj < 2; ++bj) { f32x4 v0 = acc[ai][bj][m][0] * rs, v1 = acc[ai][bj][m][1] * rs;
;                         if (sq) {
; #pragma unroll
;                             for (int j = 0; j < 4; ++j) { const float a = fmaxf(v0[j], 0.f), b = fmaxf(v1[j], 0.f); v0[j] = a * a; v1[j] = b * b; } }
;                         u32x4 w; w.x = cvtpk(v0[0], v0[1]); w.y = cvtpk(v0[2], v0[3]); w.z = cvtpk(v1[0], v1[1]); w.w = cvtpk(v1[2], v1[3]);
;                         *(u32x4*)(rowp + bj * HALF) = w; }
.LBB0_234:
	v_pk_mul_f32 v[130:131], v[126:127], v[138:139] op_sel_hi:[1,0]
	v_pk_mul_f32 v[128:129], v[124:125], v[138:139] op_sel_hi:[1,0]
	v_pk_mul_f32 v[134:135], v[122:123], v[138:139] op_sel_hi:[1,0]
	v_pk_mul_f32 v[132:133], v[120:121], v[138:139] op_sel_hi:[1,0]
	v_cndmask_b32_e64 v139, 0, 1, s[24:25]
	v_cmp_ne_u32_e64 s[0:1], 1, v139
	s_andn2_b64 vcc, exec, s[24:25]
	v_mov_b32_e32 v142, v128
	v_mov_b32_e32 v143, v129
	v_mov_b32_e32 v144, v130
	v_mov_b32_e32 v145, v131
	v_mov_b32_e32 v146, v132
	v_mov_b32_e32 v147, v133
	v_mov_b32_e32 v148, v134
	v_mov_b32_e32 v149, v135
	s_cbranch_vccnz .LBB0_236
	v_max_f32_e32 v140, 0, v128
	v_max_f32_e32 v146, 0, v132
	v_max_f32_e32 v141, 0, v129
	v_max_f32_e32 v147, 0, v133
	v_max_f32_e32 v144, 0, v130
	v_max_f32_e32 v148, 0, v134
	v_max_f32_e32 v145, 0, v131
	v_max_f32_e32 v149, 0, v135
	v_pk_mul_f32 v[142:143], v[140:141], v[140:141]
	v_pk_mul_f32 v[144:145], v[144:145], v[144:145]
	v_pk_mul_f32 v[146:147], v[146:147], v[146:147]
	v_pk_mul_f32 v[148:149], v[148:149], v[148:149]
.LBB0_236:
	v_mad_u64_u32 v[140:141], s[4:5], v214, s53, 0
	v_mov_b32_e32 v150, v141
	v_mad_u64_u32 v[150:151], s[4:5], v215, s53, v[150:151]
	v_mov_b32_e32 v141, v150
	v_ashrrev_i32_e32 v213, 31, v212
	v_lshl_add_u64 v[140:141], v[140:141], 1, s[20:21]
	v_lshl_add_u64 v[140:141], v[212:213], 1, v[140:141]
	v_mov_b32_e32 v242, v140
	v_mov_b32_e32 v243, v141
	v_cvt_pk_bf16_f32 v142, v142, v143
	v_cvt_pk_bf16_f32 v143, v144, v145
	v_cvt_pk_bf16_f32 v144, v146, v147
	v_cvt_pk_bf16_f32 v145, v148, v149
	v_mov_b32_e32 v139, v138
	global_store_dwordx4 v[140:141], v[142:145], off
	v_pk_mul_f32 v[146:147], v[116:117], v[138:139]
	s_and_b64 vcc, exec, s[0:1]
	v_mov_b32_e32 v144, v138
	v_mov_b32_e32 v145, v138
	v_pk_mul_f32 v[142:143], v[118:119], v[144:145]
	v_pk_mul_f32 v[144:145], v[114:115], v[144:145]
	v_pk_mul_f32 v[138:139], v[112:113], v[138:139]
	s_cbranch_vccnz .LBB0_238
	v_max_f32_e32 v146, 0, v146
	v_max_f32_e32 v138, 0, v138
	v_max_f32_e32 v147, 0, v147
	v_max_f32_e32 v139, 0, v139
	v_max_f32_e32 v142, 0, v142
	v_max_f32_e32 v144, 0, v144
	v_max_f32_e32 v143, 0, v143
	v_max_f32_e32 v145, 0, v145
	v_pk_mul_f32 v[146:147], v[146:147], v[146:147]
	v_pk_mul_f32 v[142:143], v[142:143], v[142:143]
	v_pk_mul_f32 v[138:139], v[138:139], v[138:139]
	v_pk_mul_f32 v[144:145], v[144:145], v[144:145]

; __device__ __forceinline__ unsigned cvtpk(float lo, float hi) { f32x2 v = {lo, hi}; bf16x2_t b = __builtin_convertvector(v, bf16x2_t); return __builtin_bit_cast(unsigned, b); }
;     __device__ __forceinline__ void operator()(AccRef acc, const Unit& u, int wr, int wc, int fr, int fq) const {
;     ...
;                 for (int m = 0; m < 4; ++m) { const int row = row0 + ai * HALF + m * 16; bf16_t* rowp = O + (size_t)row * ldc + col0;
;                     float rs = 1.f; if (nrm) rs = rsqrtf((float)rin[row] * RSS_INV + EPS);
; #pragma unroll
;                     for (int bj = 0; bj < 2; ++bj) { f32x4 v0 = acc[ai][bj][m][0] * rs, v1 = acc[ai][bj][m][1] * rs;
;                         if (sq) {
; #pragma unroll
;                             for (int j = 0; j < 4; ++j) { const float a = fmaxf(v0[j], 0.f), b = fmaxf(v1[j], 0.f); v0[j] = a * a; v1[j] = b * b; } }
;                         u32x4 w; w.x = cvtpk(v0[0], v0[1]); w.y = cvtpk(v0[2], v0[3]); w.z = cvtpk(v1[0], v1[1]); w.w = cvtpk(v1[2], v1[3]);
;                         *(u32x4*)(rowp + bj * HALF) = w; }
.LBB0_242:
	v_pk_mul_f32 v[130:131], v[110:111], v[140:141] op_sel_hi:[1,0]
	v_pk_mul_f32 v[128:129], v[108:109], v[140:141] op_sel_hi:[1,0]
	v_pk_mul_f32 v[134:135], v[106:107], v[140:141] op_sel_hi:[1,0]
	v_pk_mul_f32 v[132:133], v[104:105], v[140:141] op_sel_hi:[1,0]
	s_and_b64 vcc, exec, s[0:1]
	v_mov_b32_e32 v144, v128
	v_mov_b32_e32 v145, v129
	v_mov_b32_e32 v146, v130
	v_mov_b32_e32 v147, v131
	v_mov_b32_e32 v148, v132
	v_mov_b32_e32 v149, v133
	v_mov_b32_e32 v150, v134
	v_mov_b32_e32 v151, v135
	s_cbranch_vccnz .LBB0_244
	v_max_f32_e32 v143, 0, v133
	v_max_f32_e32 v146, 0, v130
	v_max_f32_e32 v150, 0, v134
	v_max_f32_e32 v142, 0, v132
	v_max_f32_e32 v147, 0, v131
	v_max_f32_e32 v138, 0, v128
	v_max_f32_e32 v139, 0, v129
	v_max_f32_e32 v151, 0, v135
	v_pk_mul_f32 v[144:145], v[138:139], v[138:139]
	v_pk_mul_f32 v[146:147], v[146:147], v[146:147]
	v_pk_mul_f32 v[148:149], v[142:143], v[142:143]
	v_pk_mul_f32 v[150:151], v[150:151], v[150:151]
.LBB0_244:
	v_or_b32_e32 v138, 16, v214
	s_mul_i32 s70, s53, 32
	s_mov_b32 s71, 0
	v_ashrrev_i32_e32 v139, 31, v138
	v_lshl_add_u64 v[142:143], s[70:71], 0, v[242:243]
	v_cvt_pk_bf16_f32 v144, v144, v145
	v_cvt_pk_bf16_f32 v145, v146, v147
	v_cvt_pk_bf16_f32 v146, v148, v149
	v_cvt_pk_bf16_f32 v147, v150, v151
	v_mov_b32_e32 v141, v140
	global_store_dwordx4 v[142:143], v[144:147], off
	v_pk_mul_f32 v[148:149], v[100:101], v[140:141]
	s_and_b64 vcc, exec, s[0:1]
	v_mov_b32_e32 v146, v140
	v_mov_b32_e32 v147, v140
	v_pk_mul_f32 v[144:145], v[102:103], v[146:147]
	v_pk_mul_f32 v[146:147], v[98:99], v[146:147]
	v_pk_mul_f32 v[140:141], v[96:97], v[140:141]
	s_cbranch_vccnz .LBB0_246
	v_max_f32_e32 v148, 0, v148
	v_max_f32_e32 v140, 0, v140
	v_max_f32_e32 v149, 0, v149
	v_max_f32_e32 v141, 0, v141
	v_max_f32_e32 v144, 0, v144
	v_max_f32_e32 v146, 0, v146
	v_max_f32_e32 v145, 0, v145
	v_max_f32_e32 v147, 0, v147
	v_pk_mul_f32 v[148:149], v[148:149], v[148:149]
	v_pk_mul_f32 v[144:145], v[144:145], v[144:145]
	v_pk_mul_f32 v[140:141], v[140:141], v[140:141]
	v_pk_mul_f32 v[146:147], v[146:147], v[146:147]

; __device__ __forceinline__ unsigned cvtpk(float lo, float hi) { f32x2 v = {lo, hi}; bf16x2_t b = __builtin_convertvector(v, bf16x2_t); return __builtin_bit_cast(unsigned, b); }
;     __device__ __forceinline__ void operator()(AccRef acc, const Unit& u, int wr, int wc, int fr, int fq) const {
;     ...
;                 for (int m = 0; m < 4; ++m) { const int row = row0 + ai * HALF + m * 16; bf16_t* rowp = O + (size_t)row * ldc + col0;
;                     float rs = 1.f; if (nrm) rs = rsqrtf((float)rin[row] * RSS_INV + EPS);
; #pragma unroll
;                     for (int bj = 0; bj < 2; ++bj) { f32x4 v0 = acc[ai][bj][m][0] * rs, v1 = acc[ai][bj][m][1] * rs;
;                         if (sq) {
; #pragma unroll
;                             for (int j = 0; j < 4; ++j) { const float a = fmaxf(v0[j], 0.f), b = fmaxf(v1[j], 0.f); v0[j] = a * a; v1[j] = b * b; } }
;                         u32x4 w; w.x = cvtpk(v0[0], v0[1]); w.y = cvtpk(v0[2], v0[3]); w.z = cvtpk(v1[0], v1[1]); w.w = cvtpk(v1[2], v1[3]);
;                         *(u32x4*)(rowp + bj * HALF) = w; }
.LBB0_250:
	v_pk_mul_f32 v[130:131], v[94:95], v[138:139] op_sel_hi:[1,0]
	v_pk_mul_f32 v[128:129], v[92:93], v[138:139] op_sel_hi:[1,0]
	v_pk_mul_f32 v[134:135], v[90:91], v[138:139] op_sel_hi:[1,0]
	v_pk_mul_f32 v[132:133], v[88:89], v[138:139] op_sel_hi:[1,0]
	s_and_b64 vcc, exec, s[0:1]
	v_mov_b32_e32 v144, v128
	v_mov_b32_e32 v145, v129
	v_mov_b32_e32 v146, v130
	v_mov_b32_e32 v147, v131
	v_mov_b32_e32 v148, v132
	v_mov_b32_e32 v149, v133
	v_mov_b32_e32 v150, v134
	v_mov_b32_e32 v151, v135
	s_cbranch_vccnz .LBB0_252
	v_max_f32_e32 v140, 0, v128
	v_max_f32_e32 v142, 0, v132
	v_max_f32_e32 v141, 0, v129
	v_max_f32_e32 v143, 0, v133
	v_max_f32_e32 v146, 0, v130
	v_max_f32_e32 v150, 0, v134
	v_max_f32_e32 v147, 0, v131
	v_max_f32_e32 v151, 0, v135
	v_pk_mul_f32 v[144:145], v[140:141], v[140:141]
	v_pk_mul_f32 v[146:147], v[146:147], v[146:147]
	v_pk_mul_f32 v[148:149], v[142:143], v[142:143]
	v_pk_mul_f32 v[150:151], v[150:151], v[150:151]
.LBB0_252:
	v_or_b32_e32 v140, 32, v214
	s_mul_i32 s70, s53, 64
	s_mov_b32 s71, 0
	v_ashrrev_i32_e32 v141, 31, v140
	v_lshl_add_u64 v[142:143], s[70:71], 0, v[242:243]
	v_cvt_pk_bf16_f32 v144, v144, v145
	v_cvt_pk_bf16_f32 v145, v146, v147
	v_cvt_pk_bf16_f32 v146, v148, v149
	v_cvt_pk_bf16_f32 v147, v150, v151
	v_mov_b32_e32 v139, v138
	global_store_dwordx4 v[142:143], v[144:147], off
	v_pk_mul_f32 v[148:149], v[84:85], v[138:139]
	s_and_b64 vcc, exec, s[0:1]
	v_mov_b32_e32 v146, v138
	v_mov_b32_e32 v147, v138
	v_pk_mul_f32 v[144:145], v[86:87], v[146:147]
	v_pk_mul_f32 v[146:147], v[82:83], v[146:147]
	v_pk_mul_f32 v[138:139], v[80:81], v[138:139]
	s_cbranch_vccnz .LBB0_254
	v_max_f32_e32 v148, 0, v148
	v_max_f32_e32 v138, 0, v138
	v_max_f32_e32 v149, 0, v149
	v_max_f32_e32 v139, 0, v139
	v_max_f32_e32 v144, 0, v144
	v_max_f32_e32 v146, 0, v146
	v_max_f32_e32 v145, 0, v145
	v_max_f32_e32 v147, 0, v147
	v_pk_mul_f32 v[148:149], v[148:149], v[148:149]
	v_pk_mul_f32 v[144:145], v[144:145], v[144:145]
	v_pk_mul_f32 v[138:139], v[138:139], v[138:139]
	v_pk_mul_f32 v[146:147], v[146:147], v[146:147]

; __device__ __forceinline__ unsigned cvtpk(float lo, float hi) { f32x2 v = {lo, hi}; bf16x2_t b = __builtin_convertvector(v, bf16x2_t); return __builtin_bit_cast(unsigned, b); }
;     __device__ __forceinline__ void operator()(AccRef acc, const Unit& u, int wr, int wc, int fr, int fq) const {
;     ...
;                 for (int m = 0; m < 4; ++m) { const int row = row0 + ai * HALF + m * 16; bf16_t* rowp = O + (size_t)row * ldc + col0;
;                     float rs = 1.f; if (nrm) rs = rsqrtf((float)rin[row] * RSS_INV + EPS);
; #pragma unroll
;                     for (int bj = 0; bj < 2; ++bj) { f32x4 v0 = acc[ai][bj][m][0] * rs, v1 = acc[ai][bj][m][1] * rs;
;                         if (sq) {
; #pragma unroll
;                             for (int j = 0; j < 4; ++j) { const float a = fmaxf(v0[j], 0.f), b = fmaxf(v1[j], 0.f); v0[j] = a * a; v1[j] = b * b; } }
;                         u32x4 w; w.x = cvtpk(v0[0], v0[1]); w.y = cvtpk(v0[2], v0[3]); w.z = cvtpk(v1[0], v1[1]); w.w = cvtpk(v1[2], v1[3]);
;                         *(u32x4*)(rowp + bj * HALF) = w; }
.LBB0_258:
	v_pk_mul_f32 v[130:131], v[78:79], v[138:139] op_sel_hi:[1,0]
	v_pk_mul_f32 v[128:129], v[76:77], v[138:139] op_sel_hi:[1,0]
	v_pk_mul_f32 v[134:135], v[74:75], v[138:139] op_sel_hi:[1,0]
	v_pk_mul_f32 v[132:133], v[72:73], v[138:139] op_sel_hi:[1,0]
	s_and_b64 vcc, exec, s[0:1]
	v_mov_b32_e32 v144, v128
	v_mov_b32_e32 v145, v129
	v_mov_b32_e32 v146, v130
	v_mov_b32_e32 v147, v131
	v_mov_b32_e32 v148, v132
	v_mov_b32_e32 v149, v133
	v_mov_b32_e32 v150, v134
	v_mov_b32_e32 v151, v135
	s_cbranch_vccnz .LBB0_260
	v_max_f32_e32 v140, 0, v128
	v_max_f32_e32 v142, 0, v132
	v_max_f32_e32 v141, 0, v129
	v_max_f32_e32 v143, 0, v133
	v_max_f32_e32 v146, 0, v130
	v_max_f32_e32 v150, 0, v134
	v_max_f32_e32 v147, 0, v131
	v_max_f32_e32 v151, 0, v135
	v_pk_mul_f32 v[144:145], v[140:141], v[140:141]
	v_pk_mul_f32 v[146:147], v[146:147], v[146:147]
	v_pk_mul_f32 v[148:149], v[142:143], v[142:143]
	v_pk_mul_f32 v[150:151], v[150:151], v[150:151]
.LBB0_260:
	v_or_b32_e32 v140, 48, v214
	s_mul_i32 s70, s53, 96
	s_mov_b32 s71, 0
	v_ashrrev_i32_e32 v141, 31, v140
	v_lshl_add_u64 v[142:143], s[70:71], 0, v[242:243]
	v_cvt_pk_bf16_f32 v144, v144, v145
	v_cvt_pk_bf16_f32 v145, v146, v147
	v_cvt_pk_bf16_f32 v146, v148, v149
	v_cvt_pk_bf16_f32 v147, v150, v151
	v_mov_b32_e32 v139, v138
	global_store_dwordx4 v[142:143], v[144:147], off
	v_pk_mul_f32 v[148:149], v[68:69], v[138:139]
	s_and_b64 vcc, exec, s[0:1]
	v_mov_b32_e32 v146, v138
	v_mov_b32_e32 v147, v138
	v_pk_mul_f32 v[144:145], v[70:71], v[146:147]
	v_pk_mul_f32 v[146:147], v[66:67], v[146:147]
	v_pk_mul_f32 v[138:139], v[64:65], v[138:139]
	s_cbranch_vccnz .LBB0_262
	v_max_f32_e32 v148, 0, v148
	v_max_f32_e32 v138, 0, v138
	v_max_f32_e32 v149, 0, v149
	v_max_f32_e32 v139, 0, v139
	v_max_f32_e32 v144, 0, v144
	v_max_f32_e32 v146, 0, v146
	v_max_f32_e32 v145, 0, v145
	v_max_f32_e32 v147, 0, v147
	v_pk_mul_f32 v[148:149], v[148:149], v[148:149]
	v_pk_mul_f32 v[144:145], v[144:145], v[144:145]
	v_pk_mul_f32 v[138:139], v[138:139], v[138:139]
	v_pk_mul_f32 v[146:147], v[146:147], v[146:147]

; __device__ __forceinline__ unsigned cvtpk(float lo, float hi) { f32x2 v = {lo, hi}; bf16x2_t b = __builtin_convertvector(v, bf16x2_t); return __builtin_bit_cast(unsigned, b); }
;     __device__ __forceinline__ void operator()(AccRef acc, const Unit& u, int wr, int wc, int fr, int fq) const {
;     ...
;                 for (int m = 0; m < 4; ++m) { const int row = row0 + ai * HALF + m * 16; bf16_t* rowp = O + (size_t)row * ldc + col0;
;                     float rs = 1.f; if (nrm) rs = rsqrtf((float)rin[row] * RSS_INV + EPS);
; #pragma unroll
;                     for (int bj = 0; bj < 2; ++bj) { f32x4 v0 = acc[ai][bj][m][0] * rs, v1 = acc[ai][bj][m][1] * rs;
;                         if (sq) {
; #pragma unroll
;                             for (int j = 0; j < 4; ++j) { const float a = fmaxf(v0[j], 0.f), b = fmaxf(v1[j], 0.f); v0[j] = a * a; v1[j] = b * b; } }
;                         u32x4 w; w.x = cvtpk(v0[0], v0[1]); w.y = cvtpk(v0[2], v0[3]); w.z = cvtpk(v1[0], v1[1]); w.w = cvtpk(v1[2], v1[3]);
;                         *(u32x4*)(rowp + bj * HALF) = w; }
.LBB0_266:
	v_pk_mul_f32 v[130:131], v[62:63], v[138:139] op_sel_hi:[1,0]
	v_pk_mul_f32 v[128:129], v[60:61], v[138:139] op_sel_hi:[1,0]
	v_pk_mul_f32 v[134:135], v[58:59], v[138:139] op_sel_hi:[1,0]
	v_pk_mul_f32 v[132:133], v[56:57], v[138:139] op_sel_hi:[1,0]
	s_and_b64 vcc, exec, s[0:1]
	v_mov_b32_e32 v144, v128
	v_mov_b32_e32 v145, v129
	v_mov_b32_e32 v146, v130
	v_mov_b32_e32 v147, v131
	v_mov_b32_e32 v148, v132
	v_mov_b32_e32 v149, v133
	v_mov_b32_e32 v150, v134
	v_mov_b32_e32 v151, v135
	s_cbranch_vccnz .LBB0_268
	v_max_f32_e32 v140, 0, v128
	v_max_f32_e32 v142, 0, v132
	v_max_f32_e32 v141, 0, v129
	v_max_f32_e32 v143, 0, v133
	v_max_f32_e32 v146, 0, v130
	v_max_f32_e32 v150, 0, v134
	v_max_f32_e32 v147, 0, v131
	v_max_f32_e32 v151, 0, v135
	v_pk_mul_f32 v[144:145], v[140:141], v[140:141]
	v_pk_mul_f32 v[146:147], v[146:147], v[146:147]
	v_pk_mul_f32 v[148:149], v[142:143], v[142:143]
	v_pk_mul_f32 v[150:151], v[150:151], v[150:151]
.LBB0_268:
	v_add_u32_e32 v140, 0x80, v214
	s_mul_i32 s70, s53, 256
	s_mov_b32 s71, 0
	v_ashrrev_i32_e32 v141, 31, v140
	v_lshl_add_u64 v[142:143], s[70:71], 0, v[242:243]
	v_cvt_pk_bf16_f32 v144, v144, v145
	v_cvt_pk_bf16_f32 v145, v146, v147
	v_cvt_pk_bf16_f32 v146, v148, v149
	v_cvt_pk_bf16_f32 v147, v150, v151
	v_mov_b32_e32 v139, v138
	global_store_dwordx4 v[142:143], v[144:147], off
	v_pk_mul_f32 v[148:149], v[52:53], v[138:139]
	s_and_b64 vcc, exec, s[0:1]
	v_mov_b32_e32 v146, v138
	v_mov_b32_e32 v147, v138
	v_pk_mul_f32 v[144:145], v[54:55], v[146:147]
	v_pk_mul_f32 v[146:147], v[50:51], v[146:147]
	v_pk_mul_f32 v[138:139], v[48:49], v[138:139]
	s_cbranch_vccnz .LBB0_270
	v_max_f32_e32 v148, 0, v148
	v_max_f32_e32 v138, 0, v138
	v_max_f32_e32 v149, 0, v149
	v_max_f32_e32 v139, 0, v139
	v_max_f32_e32 v144, 0, v144
	v_max_f32_e32 v146, 0, v146
	v_max_f32_e32 v145, 0, v145
	v_max_f32_e32 v147, 0, v147
	v_pk_mul_f32 v[148:149], v[148:149], v[148:149]
	v_pk_mul_f32 v[144:145], v[144:145], v[144:145]
	v_pk_mul_f32 v[138:139], v[138:139], v[138:139]
	v_pk_mul_f32 v[146:147], v[146:147], v[146:147]

; __device__ __forceinline__ unsigned cvtpk(float lo, float hi) { f32x2 v = {lo, hi}; bf16x2_t b = __builtin_convertvector(v, bf16x2_t); return __builtin_bit_cast(unsigned, b); }
;     __device__ __forceinline__ void operator()(AccRef acc, const Unit& u, int wr, int wc, int fr, int fq) const {
;     ...
;                 for (int m = 0; m < 4; ++m) { const int row = row0 + ai * HALF + m * 16; bf16_t* rowp = O + (size_t)row * ldc + col0;
;                     float rs = 1.f; if (nrm) rs = rsqrtf((float)rin[row] * RSS_INV + EPS);
; #pragma unroll
;                     for (int bj = 0; bj < 2; ++bj) { f32x4 v0 = acc[ai][bj][m][0] * rs, v1 = acc[ai][bj][m][1] * rs;
;                         if (sq) {
; #pragma unroll
;                             for (int j = 0; j < 4; ++j) { const float a = fmaxf(v0[j], 0.f), b = fmaxf(v1[j], 0.f); v0[j] = a * a; v1[j] = b * b; } }
;                         u32x4 w; w.x = cvtpk(v0[0], v0[1]); w.y = cvtpk(v0[2], v0[3]); w.z = cvtpk(v1[0], v1[1]); w.w = cvtpk(v1[2], v1[3]);
;                         *(u32x4*)(rowp + bj * HALF) = w; }
.LBB0_274:
	v_pk_mul_f32 v[130:131], v[46:47], v[138:139] op_sel_hi:[1,0]
	v_pk_mul_f32 v[128:129], v[44:45], v[138:139] op_sel_hi:[1,0]
	v_pk_mul_f32 v[134:135], v[42:43], v[138:139] op_sel_hi:[1,0]
	v_pk_mul_f32 v[132:133], v[40:41], v[138:139] op_sel_hi:[1,0]
	s_and_b64 vcc, exec, s[0:1]
	v_mov_b32_e32 v144, v128
	v_mov_b32_e32 v145, v129
	v_mov_b32_e32 v146, v130
	v_mov_b32_e32 v147, v131
	v_mov_b32_e32 v148, v132
	v_mov_b32_e32 v149, v133
	v_mov_b32_e32 v150, v134
	v_mov_b32_e32 v151, v135
	s_cbranch_vccnz .LBB0_276
	v_max_f32_e32 v140, 0, v128
	v_max_f32_e32 v142, 0, v132
	v_max_f32_e32 v141, 0, v129
	v_max_f32_e32 v143, 0, v133
	v_max_f32_e32 v146, 0, v130
	v_max_f32_e32 v150, 0, v134
	v_max_f32_e32 v147, 0, v131
	v_max_f32_e32 v151, 0, v135
	v_pk_mul_f32 v[144:145], v[140:141], v[140:141]
	v_pk_mul_f32 v[146:147], v[146:147], v[146:147]
	v_pk_mul_f32 v[148:149], v[142:143], v[142:143]
	v_pk_mul_f32 v[150:151], v[150:151], v[150:151]
.LBB0_276:
	v_add_u32_e32 v140, 0x90, v214
	s_mul_i32 s70, s53, 288
	s_mov_b32 s71, 0
	v_ashrrev_i32_e32 v141, 31, v140
	v_lshl_add_u64 v[142:143], s[70:71], 0, v[242:243]
	v_cvt_pk_bf16_f32 v144, v144, v145
	v_cvt_pk_bf16_f32 v145, v146, v147
	v_cvt_pk_bf16_f32 v146, v148, v149
	v_cvt_pk_bf16_f32 v147, v150, v151
	v_mov_b32_e32 v139, v138
	global_store_dwordx4 v[142:143], v[144:147], off
	v_pk_mul_f32 v[148:149], v[36:37], v[138:139]
	s_and_b64 vcc, exec, s[0:1]
	v_mov_b32_e32 v146, v138
	v_mov_b32_e32 v147, v138
	v_pk_mul_f32 v[144:145], v[38:39], v[146:147]
	v_pk_mul_f32 v[146:147], v[34:35], v[146:147]
	v_pk_mul_f32 v[138:139], v[32:33], v[138:139]
	s_cbranch_vccnz .LBB0_278
	v_max_f32_e32 v148, 0, v148
	v_max_f32_e32 v138, 0, v138
	v_max_f32_e32 v149, 0, v149
	v_max_f32_e32 v139, 0, v139
	v_max_f32_e32 v144, 0, v144
	v_max_f32_e32 v146, 0, v146
	v_max_f32_e32 v145, 0, v145
	v_max_f32_e32 v147, 0, v147
	v_pk_mul_f32 v[148:149], v[148:149], v[148:149]
	v_pk_mul_f32 v[144:145], v[144:145], v[144:145]
	v_pk_mul_f32 v[138:139], v[138:139], v[138:139]
	v_pk_mul_f32 v[146:147], v[146:147], v[146:147]

; __device__ __forceinline__ unsigned cvtpk(float lo, float hi) { f32x2 v = {lo, hi}; bf16x2_t b = __builtin_convertvector(v, bf16x2_t); return __builtin_bit_cast(unsigned, b); }
;     __device__ __forceinline__ void operator()(AccRef acc, const Unit& u, int wr, int wc, int fr, int fq) const {
;     ...
;                 for (int m = 0; m < 4; ++m) { const int row = row0 + ai * HALF + m * 16; bf16_t* rowp = O + (size_t)row * ldc + col0;
;                     float rs = 1.f; if (nrm) rs = rsqrtf((float)rin[row] * RSS_INV + EPS);
; #pragma unroll
;                     for (int bj = 0; bj < 2; ++bj) { f32x4 v0 = acc[ai][bj][m][0] * rs, v1 = acc[ai][bj][m][1] * rs;
;                         if (sq) {
; #pragma unroll
;                             for (int j = 0; j < 4; ++j) { const float a = fmaxf(v0[j], 0.f), b = fmaxf(v1[j], 0.f); v0[j] = a * a; v1[j] = b * b; } }
;                         u32x4 w; w.x = cvtpk(v0[0], v0[1]); w.y = cvtpk(v0[2], v0[3]); w.z = cvtpk(v1[0], v1[1]); w.w = cvtpk(v1[2], v1[3]);
;                         *(u32x4*)(rowp + bj * HALF) = w; }
.LBB0_282:
	v_pk_mul_f32 v[130:131], v[30:31], v[138:139] op_sel_hi:[1,0]
	v_pk_mul_f32 v[128:129], v[28:29], v[138:139] op_sel_hi:[1,0]
	v_pk_mul_f32 v[134:135], v[26:27], v[138:139] op_sel_hi:[1,0]
	v_pk_mul_f32 v[132:133], v[24:25], v[138:139] op_sel_hi:[1,0]
	s_and_b64 vcc, exec, s[0:1]
	v_mov_b32_e32 v144, v128
	v_mov_b32_e32 v145, v129
	v_mov_b32_e32 v146, v130
	v_mov_b32_e32 v147, v131
	v_mov_b32_e32 v148, v132
	v_mov_b32_e32 v149, v133
	v_mov_b32_e32 v150, v134
	v_mov_b32_e32 v151, v135
	s_cbranch_vccnz .LBB0_284
	v_max_f32_e32 v140, 0, v128
	v_max_f32_e32 v142, 0, v132
	v_max_f32_e32 v141, 0, v129
	v_max_f32_e32 v143, 0, v133
	v_max_f32_e32 v146, 0, v130
	v_max_f32_e32 v150, 0, v134
	v_max_f32_e32 v147, 0, v131
	v_max_f32_e32 v151, 0, v135
	v_pk_mul_f32 v[144:145], v[140:141], v[140:141]
	v_pk_mul_f32 v[146:147], v[146:147], v[146:147]
	v_pk_mul_f32 v[148:149], v[142:143], v[142:143]
	v_pk_mul_f32 v[150:151], v[150:151], v[150:151]
.LBB0_284:
	v_add_u32_e32 v140, 0xa0, v214
	s_mul_i32 s70, s53, 320
	s_mov_b32 s71, 0
	v_ashrrev_i32_e32 v141, 31, v140
	v_lshl_add_u64 v[142:143], s[70:71], 0, v[242:243]
	v_cvt_pk_bf16_f32 v144, v144, v145
	v_cvt_pk_bf16_f32 v145, v146, v147
	v_cvt_pk_bf16_f32 v146, v148, v149
	v_cvt_pk_bf16_f32 v147, v150, v151
	v_mov_b32_e32 v139, v138
	global_store_dwordx4 v[142:143], v[144:147], off
	v_pk_mul_f32 v[148:149], v[20:21], v[138:139]
	s_and_b64 vcc, exec, s[0:1]
	v_mov_b32_e32 v146, v138
	v_mov_b32_e32 v147, v138
	v_pk_mul_f32 v[144:145], v[22:23], v[146:147]
	v_pk_mul_f32 v[146:147], v[18:19], v[146:147]
	v_pk_mul_f32 v[138:139], v[16:17], v[138:139]
	s_cbranch_vccnz .LBB0_286
	v_max_f32_e32 v148, 0, v148
	v_max_f32_e32 v138, 0, v138
	v_max_f32_e32 v149, 0, v149
	v_max_f32_e32 v139, 0, v139
	v_max_f32_e32 v144, 0, v144
	v_max_f32_e32 v146, 0, v146
	v_max_f32_e32 v145, 0, v145
	v_max_f32_e32 v147, 0, v147
	v_pk_mul_f32 v[148:149], v[148:149], v[148:149]
	v_pk_mul_f32 v[144:145], v[144:145], v[144:145]
	v_pk_mul_f32 v[138:139], v[138:139], v[138:139]
	v_pk_mul_f32 v[146:147], v[146:147], v[146:147]

; __device__ __forceinline__ unsigned cvtpk(float lo, float hi) { f32x2 v = {lo, hi}; bf16x2_t b = __builtin_convertvector(v, bf16x2_t); return __builtin_bit_cast(unsigned, b); }
;     __device__ __forceinline__ void operator()(AccRef acc, const Unit& u, int wr, int wc, int fr, int fq) const {
;     ...
;                 for (int m = 0; m < 4; ++m) { const int row = row0 + ai * HALF + m * 16; bf16_t* rowp = O + (size_t)row * ldc + col0;
;                     float rs = 1.f; if (nrm) rs = rsqrtf((float)rin[row] * RSS_INV + EPS);
; #pragma unroll
;                     for (int bj = 0; bj < 2; ++bj) { f32x4 v0 = acc[ai][bj][m][0] * rs, v1 = acc[ai][bj][m][1] * rs;
;                         if (sq) {
; #pragma unroll
;                             for (int j = 0; j < 4; ++j) { const float a = fmaxf(v0[j], 0.f), b = fmaxf(v1[j], 0.f); v0[j] = a * a; v1[j] = b * b; } }
;                         u32x4 w; w.x = cvtpk(v0[0], v0[1]); w.y = cvtpk(v0[2], v0[3]); w.z = cvtpk(v1[0], v1[1]); w.w = cvtpk(v1[2], v1[3]);
;                         *(u32x4*)(rowp + bj * HALF) = w; }
.LBB0_290:
	v_pk_mul_f32 v[130:131], v[14:15], v[138:139] op_sel_hi:[1,0]
	v_pk_mul_f32 v[128:129], v[12:13], v[138:139] op_sel_hi:[1,0]
	v_pk_mul_f32 v[134:135], v[10:11], v[138:139] op_sel_hi:[1,0]
	v_pk_mul_f32 v[132:133], v[8:9], v[138:139] op_sel_hi:[1,0]
	s_and_b64 vcc, exec, s[0:1]
	v_mov_b32_e32 v142, v128
	v_mov_b32_e32 v143, v129
	v_mov_b32_e32 v144, v130
	v_mov_b32_e32 v145, v131
	v_mov_b32_e32 v146, v132
	v_mov_b32_e32 v147, v133
	v_mov_b32_e32 v148, v134
	v_mov_b32_e32 v149, v135
	s_cbranch_vccnz .LBB0_292
	v_max_f32_e32 v141, 0, v133
	v_max_f32_e32 v144, 0, v130
	v_max_f32_e32 v148, 0, v134
	v_max_f32_e32 v140, 0, v132
	v_max_f32_e32 v145, 0, v131
	v_max_f32_e32 v136, 0, v128
	v_max_f32_e32 v137, 0, v129
	v_max_f32_e32 v149, 0, v135
	v_pk_mul_f32 v[142:143], v[136:137], v[136:137]
	v_pk_mul_f32 v[144:145], v[144:145], v[144:145]
	v_pk_mul_f32 v[146:147], v[140:141], v[140:141]
	v_pk_mul_f32 v[148:149], v[148:149], v[148:149]
.LBB0_292:
	v_add_u32_e32 v136, 0xb0, v214
	s_mul_i32 s6, s53, 352
	s_mov_b32 s7, 0
	v_ashrrev_i32_e32 v137, 31, v136
	v_lshl_add_u64 v[140:141], s[6:7], 0, v[242:243]
	v_cvt_pk_bf16_f32 v142, v142, v143
	v_cvt_pk_bf16_f32 v143, v144, v145
	v_cvt_pk_bf16_f32 v144, v146, v147
	v_cvt_pk_bf16_f32 v145, v148, v149
	v_mov_b32_e32 v139, v138
	global_store_dwordx4 v[140:141], v[142:145], off
	v_pk_mul_f32 v[146:147], v[4:5], v[138:139]
	s_and_b64 vcc, exec, s[0:1]
	v_mov_b32_e32 v144, v138
	v_mov_b32_e32 v145, v138
	v_pk_mul_f32 v[142:143], v[6:7], v[144:145]
	v_pk_mul_f32 v[144:145], v[2:3], v[144:145]
	v_pk_mul_f32 v[138:139], v[0:1], v[138:139]
	s_cbranch_vccnz .LBB0_294
	v_max_f32_e32 v146, 0, v146
	v_max_f32_e32 v138, 0, v138
	v_max_f32_e32 v147, 0, v147
	v_max_f32_e32 v139, 0, v139
	v_max_f32_e32 v142, 0, v142
	v_max_f32_e32 v144, 0, v144
	v_max_f32_e32 v143, 0, v143
	v_max_f32_e32 v145, 0, v145
	v_pk_mul_f32 v[146:147], v[146:147], v[146:147]
	v_pk_mul_f32 v[142:143], v[142:143], v[142:143]
	v_pk_mul_f32 v[138:139], v[138:139], v[138:139]
	v_pk_mul_f32 v[144:145], v[144:145], v[144:145]
